# attention: both LDS-DMA tile loads issued behind the first MFMA of the block (half a block more landing time), stock rings and waits
# speedup vs baseline: 1.0072x; 1.0071x over previous
; #define WAIT_BAR(N) asm volatile("s_waitcnt vmcnt(" #N ") lgkmcnt(0)\n\ts_barrier":::"memory")
;   #define RESC() do{}while(0)
;   #define ROT() do{sl_prev=sl_cur;sl_cur=sl_next;sl_next=(sl_next==(NSLOT-1)*SLOTB)?0:sl_next+SLOTB;}while(0)
; template<int THRL> __device__ __forceinline__ void attn_unit(int b,int h,int qb,const bf16*Q,const bf16*__restrict__ K,const bf16*__restrict__ V,bf16*O,char*shm,float m2){
;     ...
;   int t=1;
;   for(;t+5<NT;t+=2){
;     STEP(pB0,pB1,pA0,pA1,t,true,true,true);     WAIT_BAR(2); RESC(); ROT();
.LBB0_829:
	v_add_u32_e32 v190, s17, v220
	ds_read_b64_tr_b16 v[230:231], v190 offset:24576
	ds_read_b64_tr_b16 v[232:233], v190 offset:25088
	s_waitcnt lgkmcnt(9)
	v_mfma_f32_32x32x16_bf16 v[114:129], v[98:101], v[174:177], v[50:65]
	v_exp_f32_e32 v78, v78
	v_lshl_add_u64 v[238:239], v[214:215], 0, s[48:49]
	s_add_i32 s98, s16, s12
	s_mov_b32 s99, m0
	s_mov_b32 m0, s98
	s_nop 0
	global_load_lds_dwordx4 v[238:239], off
	s_mov_b32 m0, s99
	v_lshl_add_u64 v[238:239], v[216:217], 0, s[42:43]
	s_add_i32 s98, s15, s4
	s_mov_b32 m0, s98
	s_nop 0
	global_load_lds_dwordx4 v[238:239], off
	s_mov_b32 m0, s99
	v_add_f32_e32 v102, v82, v83
	v_add_f32_e32 v102, v84, v102
	v_add_f32_e32 v102, v85, v102
	v_add_f32_e32 v102, v86, v102
	v_add_f32_e32 v102, v87, v102
	v_cvt_pk_bf16_f32 v166, v82, v83
	v_cvt_pk_bf16_f32 v167, v84, v85
	ds_read_b64_tr_b16 v[82:83], v190 offset:28672
	ds_read_b64_tr_b16 v[84:85], v190 offset:29184
	v_add_f32_e32 v98, v88, v102
	v_add_f32_e32 v98, v89, v98
	v_add_f32_e32 v98, v90, v98
	v_add_f32_e32 v146, v91, v98
	s_waitcnt lgkmcnt(10)
	v_mfma_f32_32x32x16_bf16 v[98:113], v[182:185], v[174:177], v[50:65]
	v_exp_f32_e32 v79, v79
	v_cvt_pk_bf16_f32 v168, v86, v87
	v_cvt_pk_bf16_f32 v169, v88, v89
	ds_read_b64_tr_b16 v[86:87], v190 offset:25600
	ds_read_b64_tr_b16 v[88:89], v190 offset:26112
	v_add_f32_e32 v146, v92, v146
	v_add_f32_e32 v146, v93, v146
	v_add_f32_e32 v146, v94, v146
	v_add_f32_e32 v146, v95, v146
	v_cvt_pk_bf16_f32 v158, v90, v91
	v_cvt_pk_bf16_f32 v159, v92, v93
	s_waitcnt lgkmcnt(11)
	v_mfma_f32_32x32x16_bf16 v[114:129], v[186:189], v[170:173], v[114:129]
	v_exp_f32_e32 v80, v80
	ds_read_b64_tr_b16 v[90:91], v190 offset:29696
	ds_read_b64_tr_b16 v[92:93], v190 offset:30208
	s_waitcnt lgkmcnt(12)
	v_mfma_f32_32x32x16_bf16 v[98:113], v[178:181], v[170:173], v[98:113]
	v_exp_f32_e32 v81, v81
	v_add_f32_e32 v146, v96, v146
	v_add_f32_e32 v146, v97, v146
	v_add_f32_e32 v146, v66, v146
	v_add_f32_e32 v146, v67, v146
	v_cvt_pk_bf16_f32 v160, v94, v95
	v_cvt_pk_bf16_f32 v161, v96, v97
	ds_read_b64_tr_b16 v[94:95], v190 offset:26624
	ds_read_b64_tr_b16 v[96:97], v190 offset:27136
	s_waitcnt lgkmcnt(13)
	v_mfma_f32_32x32x16_bf16 v[114:129], v[142:145], v[162:165], v[114:129]
	v_add_f32_e32 v142, v68, v146
	v_add_f32_e32 v142, v69, v142
	v_add_f32_e32 v142, v70, v142
	v_add_f32_e32 v142, v71, v142
	v_cvt_pk_bf16_f32 v150, v66, v67
	v_cvt_pk_bf16_f32 v151, v68, v69
	ds_read_b64_tr_b16 v[66:67], v190 offset:30720
	ds_read_b64_tr_b16 v[68:69], v190 offset:31232
	s_waitcnt lgkmcnt(14)
	v_mfma_f32_32x32x16_bf16 v[98:113], v[138:141], v[162:165], v[98:113]
	v_add_f32_e32 v138, v72, v142
	v_add_f32_e32 v138, v73, v138
	v_add_f32_e32 v138, v74, v138
	v_add_f32_e32 v138, v75, v138
	v_cvt_pk_bf16_f32 v152, v70, v71
	v_cvt_pk_bf16_f32 v153, v72, v73
	ds_read_b64_tr_b16 v[70:71], v190 offset:27648
	ds_read_b64_tr_b16 v[72:73], v190 offset:28160
	s_waitcnt lgkmcnt(14)
	v_mfma_f32_32x32x16_bf16 v[114:129], v[134:137], v[154:157], v[114:129]
	v_add_f32_e32 v134, v76, v138
	v_add_f32_e32 v134, v77, v134
	v_add_f32_e32 v134, v78, v134
	v_add_f32_e32 v134, v79, v134
	v_cvt_pk_bf16_f32 v146, v74, v75
	v_cvt_pk_bf16_f32 v147, v76, v77
	ds_read_b64_tr_b16 v[74:75], v190 offset:31744
	ds_read_b64_tr_b16 v[76:77], v190 offset:32256
	v_mfma_f32_32x32x16_bf16 v[98:113], v[130:133], v[154:157], v[98:113]
	v_add_f32_e32 v130, v80, v134
	v_add_f32_e32 v130, v81, v130
	v_add_f32_e32 v130, 0, v130
	v_cvt_pk_bf16_f32 v148, v78, v79
	v_cvt_pk_bf16_f32 v149, v80, v81
	v_add_f32_e32 v190, v199, v130
	s_waitcnt lgkmcnt(14)
	v_mfma_f32_32x32x16_bf16 v[18:33], v[166:169], v[230:233], v[18:33]
	v_exp_f32_e32 v114, v114
	v_exp_f32_e32 v115, v115
	v_exp_f32_e32 v116, v116
	v_exp_f32_e32 v117, v117
	s_waitcnt lgkmcnt(12)
	v_mfma_f32_32x32x16_bf16 v[34:49], v[166:169], v[82:85], v[34:49]
	v_exp_f32_e32 v118, v118
	v_exp_f32_e32 v119, v119
	v_exp_f32_e32 v120, v120
	v_exp_f32_e32 v121, v121
	v_add_u32_e32 v82, s15, v219
	ds_read_b128 v[78:81], v82
	ds_read_b128 v[134:137], v82 offset:512
	s_waitcnt lgkmcnt(12)
	v_mfma_f32_32x32x16_bf16 v[18:33], v[158:161], v[86:89], v[18:33]
	v_exp_f32_e32 v122, v122
	v_exp_f32_e32 v123, v123
	v_exp_f32_e32 v124, v124
	v_exp_f32_e32 v125, v125
	ds_read_b128 v[138:141], v82 offset:2048
	ds_read_b128 v[142:145], v82 offset:2560
	s_waitcnt lgkmcnt(12)
	v_mfma_f32_32x32x16_bf16 v[34:49], v[158:161], v[90:93], v[34:49]
	v_exp_f32_e32 v126, v126
	v_exp_f32_e32 v127, v127
	v_exp_f32_e32 v128, v128
	v_exp_f32_e32 v129, v129
	ds_read_b128 v[178:181], v82 offset:4096
	ds_read_b128 v[182:185], v82 offset:4608
	s_waitcnt lgkmcnt(12)
	v_mfma_f32_32x32x16_bf16 v[18:33], v[150:153], v[94:97], v[18:33]
	v_exp_f32_e32 v98, v98
	v_exp_f32_e32 v99, v99
	v_exp_f32_e32 v100, v100
	v_exp_f32_e32 v101, v101
	ds_read_b128 v[186:189], v82 offset:6144
	ds_read_b128 v[130:133], v82 offset:6656
	s_waitcnt lgkmcnt(12)
	v_mfma_f32_32x32x16_bf16 v[34:49], v[150:153], v[66:69], v[34:49]
	v_exp_f32_e32 v102, v102
	v_exp_f32_e32 v103, v103
	v_exp_f32_e32 v104, v104
	v_exp_f32_e32 v105, v105
	s_waitcnt lgkmcnt(10)
	v_mfma_f32_32x32x16_bf16 v[18:33], v[146:149], v[70:73], v[18:33]
	v_exp_f32_e32 v106, v106
	v_exp_f32_e32 v107, v107
	v_exp_f32_e32 v108, v108
	v_exp_f32_e32 v109, v109
	s_waitcnt lgkmcnt(8)
	v_mfma_f32_32x32x16_bf16 v[34:49], v[146:149], v[74:77], v[34:49]
	s_waitcnt vmcnt(2) lgkmcnt(0)
	s_barrier
; #define WAIT_BAR(N) asm volatile("s_waitcnt vmcnt(" #N ") lgkmcnt(0)\n\ts_barrier":::"memory")
;   #define RESC() do{}while(0)
;   #define ROT() do{sl_prev=sl_cur;sl_cur=sl_next;sl_next=(sl_next==(NSLOT-1)*SLOTB)?0:sl_next+SLOTB;}while(0)
; template<int THRL> __device__ __forceinline__ void attn_unit(int b,int h,int qb,const bf16*Q,const bf16*__restrict__ K,const bf16*__restrict__ V,bf16*O,char*shm,float m2){
;     ...
;   int t=1;
;   for(;t+5<NT;t+=2){
;     STEP(pB0,pB1,pA0,pA1,t,true,true,true);     WAIT_BAR(2); RESC(); ROT();
;     STEP(pA0,pA1,pB0,pB1,t+1,true,true,true);   WAIT_BAR(2); RESC(); ROT();
	s_add_i32 s0, s15, 0x2000
	s_cmpk_lg_i32 s15, 0x4000
	s_cselect_b32 s0, s0, 0
	v_add_u32_e32 v199, s16, v220
	ds_read_b64_tr_b16 v[230:231], v199 offset:24576
	ds_read_b64_tr_b16 v[232:233], v199 offset:25088
	s_waitcnt lgkmcnt(9)
	v_mfma_f32_32x32x16_bf16 v[82:97], v[78:81], v[174:177], v[50:65]
	v_exp_f32_e32 v110, v110
	s_mov_b64 s[100:101], 0x10000
	v_lshl_add_u64 v[238:239], v[214:215], 0, s[100:101]
	s_add_i32 s98, s15, s12
	s_mov_b32 s99, m0
	s_mov_b32 m0, s98
	s_nop 0
	global_load_lds_dwordx4 v[238:239], off
	s_mov_b32 m0, s99
	v_lshl_add_u64 v[216:217], v[216:217], 0, s[46:47]
	s_add_i32 s98, s0, s4
	s_mov_b32 m0, s98
	s_nop 0
	global_load_lds_dwordx4 v[216:217], off
	s_mov_b32 m0, s99
	v_add_f32_e32 v66, v114, v115
	v_add_f32_e32 v66, v116, v66
	v_add_f32_e32 v66, v117, v66
	v_add_f32_e32 v66, v118, v66
	v_add_f32_e32 v66, v119, v66
	v_cvt_pk_bf16_f32 v166, v114, v115
	v_cvt_pk_bf16_f32 v167, v116, v117
	ds_read_b64_tr_b16 v[114:115], v199 offset:28672
	ds_read_b64_tr_b16 v[116:117], v199 offset:29184
	v_add_f32_e32 v66, v120, v66
	v_add_f32_e32 v66, v121, v66
	v_add_f32_e32 v66, v122, v66
	v_add_f32_e32 v146, v123, v66
	s_waitcnt lgkmcnt(10)
	v_mfma_f32_32x32x16_bf16 v[66:81], v[134:137], v[174:177], v[50:65]
	v_exp_f32_e32 v111, v111
	v_cvt_pk_bf16_f32 v168, v118, v119
	v_cvt_pk_bf16_f32 v169, v120, v121
	ds_read_b64_tr_b16 v[118:119], v199 offset:25600
	ds_read_b64_tr_b16 v[120:121], v199 offset:26112
	s_waitcnt lgkmcnt(11)
	v_mfma_f32_32x32x16_bf16 v[82:97], v[138:141], v[170:173], v[82:97]
	v_exp_f32_e32 v112, v112
	v_add_f32_e32 v134, v124, v146
	v_add_f32_e32 v134, v125, v134
	v_add_f32_e32 v134, v126, v134
	v_add_f32_e32 v134, v127, v134
	v_cvt_pk_bf16_f32 v158, v122, v123
	v_cvt_pk_bf16_f32 v159, v124, v125
	ds_read_b64_tr_b16 v[122:123], v199 offset:29696
	ds_read_b64_tr_b16 v[124:125], v199 offset:30208
	s_waitcnt lgkmcnt(12)
	v_mfma_f32_32x32x16_bf16 v[66:81], v[142:145], v[170:173], v[66:81]
	v_exp_f32_e32 v113, v113
	v_add_f32_e32 v134, v128, v134
	v_add_f32_e32 v134, v129, v134
	v_add_f32_e32 v134, v98, v134
	v_add_f32_e32 v134, v99, v134
	v_cvt_pk_bf16_f32 v160, v126, v127
	v_cvt_pk_bf16_f32 v161, v128, v129
	ds_read_b64_tr_b16 v[126:127], v199 offset:26624
	ds_read_b64_tr_b16 v[128:129], v199 offset:27136
	s_waitcnt lgkmcnt(13)
	v_mfma_f32_32x32x16_bf16 v[82:97], v[178:181], v[162:165], v[82:97]
	v_add_f32_e32 v134, v100, v134
	v_add_f32_e32 v134, v101, v134
	v_add_f32_e32 v134, v102, v134
	v_add_f32_e32 v134, v103, v134
	v_cvt_pk_bf16_f32 v150, v98, v99
	v_cvt_pk_bf16_f32 v151, v100, v101
	ds_read_b64_tr_b16 v[234:235], v199 offset:30720
	ds_read_b64_tr_b16 v[236:237], v199 offset:31232
	s_waitcnt lgkmcnt(14)
	v_mfma_f32_32x32x16_bf16 v[66:81], v[182:185], v[162:165], v[66:81]
	v_add_f32_e32 v98, v104, v134
	v_add_f32_e32 v98, v105, v98
	v_add_f32_e32 v98, v106, v98
	v_add_f32_e32 v98, v107, v98
	v_cvt_pk_bf16_f32 v152, v102, v103
	v_cvt_pk_bf16_f32 v153, v104, v105
	ds_read_b64_tr_b16 v[102:103], v199 offset:27648
	ds_read_b64_tr_b16 v[104:105], v199 offset:28160
	s_waitcnt lgkmcnt(14)
	v_mfma_f32_32x32x16_bf16 v[82:97], v[186:189], v[154:157], v[82:97]
	v_add_f32_e32 v98, v108, v98
	v_add_f32_e32 v98, v109, v98
	v_add_f32_e32 v98, v110, v98
	v_add_f32_e32 v98, v111, v98
	v_cvt_pk_bf16_f32 v146, v106, v107
	v_cvt_pk_bf16_f32 v147, v108, v109
	ds_read_b64_tr_b16 v[106:107], v199 offset:31744
	ds_read_b64_tr_b16 v[108:109], v199 offset:32256
	v_mfma_f32_32x32x16_bf16 v[66:81], v[130:133], v[154:157], v[66:81]
	v_add_f32_e32 v98, v112, v98
	v_add_f32_e32 v98, v113, v98
	v_add_f32_e32 v98, 0, v98
	v_cvt_pk_bf16_f32 v148, v110, v111
	v_cvt_pk_bf16_f32 v149, v112, v113
	v_add_f32_e32 v199, v190, v98
	s_waitcnt lgkmcnt(14)
	v_mfma_f32_32x32x16_bf16 v[18:33], v[166:169], v[230:233], v[18:33]
	v_exp_f32_e32 v82, v82
	v_exp_f32_e32 v83, v83
	v_exp_f32_e32 v84, v84
	v_exp_f32_e32 v85, v85
	s_waitcnt lgkmcnt(12)
	v_mfma_f32_32x32x16_bf16 v[34:49], v[166:169], v[114:117], v[34:49]
	v_exp_f32_e32 v86, v86
	v_exp_f32_e32 v87, v87
	v_exp_f32_e32 v88, v88
	v_exp_f32_e32 v89, v89
	v_add_u32_e32 v110, s0, v219
	ds_read_b128 v[98:101], v110
	ds_read_b128 v[182:185], v110 offset:512
	s_waitcnt lgkmcnt(12)
	v_mfma_f32_32x32x16_bf16 v[18:33], v[158:161], v[118:121], v[18:33]
	v_exp_f32_e32 v90, v90
	v_exp_f32_e32 v91, v91
	v_exp_f32_e32 v92, v92
	v_exp_f32_e32 v93, v93
	ds_read_b128 v[186:189], v110 offset:2048
	ds_read_b128 v[178:181], v110 offset:2560
	s_waitcnt lgkmcnt(12)
	v_mfma_f32_32x32x16_bf16 v[34:49], v[158:161], v[122:125], v[34:49]
	v_exp_f32_e32 v94, v94
	v_exp_f32_e32 v95, v95
	v_exp_f32_e32 v96, v96
	v_exp_f32_e32 v97, v97
	ds_read_b128 v[142:145], v110 offset:4096
	ds_read_b128 v[138:141], v110 offset:4608
	s_waitcnt lgkmcnt(12)
	v_mfma_f32_32x32x16_bf16 v[18:33], v[150:153], v[126:129], v[18:33]
	v_exp_f32_e32 v66, v66
	v_exp_f32_e32 v67, v67
	v_exp_f32_e32 v68, v68
	v_exp_f32_e32 v69, v69
	ds_read_b128 v[134:137], v110 offset:6144
	ds_read_b128 v[130:133], v110 offset:6656
	s_waitcnt lgkmcnt(12)
	v_mfma_f32_32x32x16_bf16 v[34:49], v[150:153], v[234:237], v[34:49]
	v_exp_f32_e32 v70, v70
	v_exp_f32_e32 v71, v71
	v_exp_f32_e32 v72, v72
	v_exp_f32_e32 v73, v73
	s_waitcnt lgkmcnt(10)
	v_mfma_f32_32x32x16_bf16 v[18:33], v[146:149], v[102:105], v[18:33]
	v_exp_f32_e32 v74, v74
	v_exp_f32_e32 v75, v75
	v_exp_f32_e32 v76, v76
	v_exp_f32_e32 v77, v77
	s_waitcnt lgkmcnt(8)
	v_mfma_f32_32x32x16_bf16 v[34:49], v[146:149], v[106:109], v[34:49]
	s_add_i32 s18, s0, 0x2000
	s_waitcnt vmcnt(2) lgkmcnt(0)
	s_barrier
	s_cmpk_lg_i32 s0, 0x4000
	s_mov_b32 s17, s15
	s_cselect_b32 s15, s18, 0
	s_add_i32 s14, s14, 2
	v_lshl_add_u64 v[214:215], v[214:215], 0, s[46:47]
	s_mov_b32 s16, s0
	s_cmpk_gt_u32 s14, 0x78
	s_cbranch_scc0 .LBB0_829
;   #define RESC() do{}while(0)
;   #define ROT() do{sl_prev=sl_cur;sl_cur=sl_next;sl_next=(sl_next==(NSLOT-1)*SLOTB)?0:sl_next+SLOTB;}while(0)
;   #define ENDW(tt) do{ if((tt)+3<NT){WAIT_BAR(2);} else if((tt)+2<NT){WAIT_BAR(1);} else {WAIT_BAR(0);} }while(0)
; template<int THRL> __device__ __forceinline__ void attn_unit(int b,int h,int qb,const bf16*Q,const bf16*__restrict__ K,const bf16*__restrict__ V,bf16*O,char*shm,float m2){
;     ...
;   for(;t+1<NT;t+=2){
;     STEP(pB0,pB1,pA0,pA1,t,(t+3<NT),(t+1<NT),(t+1<NT));       ENDW(t);   RESC(); ROT();
;     STEP(pA0,pA1,pB0,pB1,t+1,(t+4<NT),(t+2<NT),(t+2<NT));     ENDW(t+1); RESC(); ROT();
	v_exp_f32_e32 v78, v78
	v_exp_f32_e32 v79, v79
	v_exp_f32_e32 v80, v80
	v_exp_f32_e32 v81, v81
	s_and_b32 s0, s13, 0x3fffffc0
	s_lshl_b32 s0, s0, 2
	s_add_i32 s0, s0, 0
	ds_read_b64_tr_b16 v[214:215], v220 offset:40960
	ds_read_b64_tr_b16 v[216:217], v220 offset:41472
	v_add_f32_e32 v102, v82, v83
	v_add_f32_e32 v102, v84, v102
	v_add_f32_e32 v102, v85, v102
	v_add_f32_e32 v102, v86, v102
	v_add_f32_e32 v102, v87, v102
	v_cvt_pk_bf16_f32 v166, v82, v83
	v_cvt_pk_bf16_f32 v167, v84, v85
	s_waitcnt lgkmcnt(9)
	v_mfma_f32_32x32x16_bf16 v[114:129], v[98:101], v[174:177], v[50:65]
	ds_read_b64_tr_b16 v[82:83], v220 offset:45056
	ds_read_b64_tr_b16 v[84:85], v220 offset:45568
	v_add_f32_e32 v98, v88, v102
	v_add_f32_e32 v98, v89, v98
	v_add_f32_e32 v98, v90, v98
	v_add_f32_e32 v146, v91, v98
	v_cvt_pk_bf16_f32 v168, v86, v87
	v_cvt_pk_bf16_f32 v169, v88, v89
	s_waitcnt lgkmcnt(10)
	v_mfma_f32_32x32x16_bf16 v[98:113], v[182:185], v[174:177], v[50:65]
	ds_read_b64_tr_b16 v[86:87], v220 offset:41984
	ds_read_b64_tr_b16 v[88:89], v220 offset:42496
	v_add_f32_e32 v146, v92, v146
	v_add_f32_e32 v146, v93, v146
	v_add_f32_e32 v146, v94, v146
	v_add_f32_e32 v146, v95, v146
	v_cvt_pk_bf16_f32 v158, v90, v91
	v_cvt_pk_bf16_f32 v159, v92, v93
	s_waitcnt lgkmcnt(11)
	v_mfma_f32_32x32x16_bf16 v[114:129], v[186:189], v[170:173], v[114:129]
	ds_read_b64_tr_b16 v[90:91], v220 offset:46080
	ds_read_b64_tr_b16 v[92:93], v220 offset:46592
	v_add_f32_e32 v146, v96, v146
	v_add_f32_e32 v146, v97, v146
	v_add_f32_e32 v146, v66, v146
	v_add_f32_e32 v146, v67, v146
	v_cvt_pk_bf16_f32 v160, v94, v95
	v_cvt_pk_bf16_f32 v161, v96, v97
	s_waitcnt lgkmcnt(12)
	v_mfma_f32_32x32x16_bf16 v[98:113], v[178:181], v[170:173], v[98:113]
	ds_read_b64_tr_b16 v[94:95], v220 offset:43008
	ds_read_b64_tr_b16 v[96:97], v220 offset:43520
	s_waitcnt lgkmcnt(13)
	v_mfma_f32_32x32x16_bf16 v[114:129], v[142:145], v[162:165], v[114:129]
	v_add_f32_e32 v142, v68, v146
	v_add_f32_e32 v142, v69, v142
	v_add_f32_e32 v142, v70, v142
	v_add_f32_e32 v142, v71, v142
	v_cvt_pk_bf16_f32 v150, v66, v67
	v_cvt_pk_bf16_f32 v151, v68, v69
	ds_read_b64_tr_b16 v[66:67], v220 offset:47104
	ds_read_b64_tr_b16 v[68:69], v220 offset:47616
	s_waitcnt lgkmcnt(14)
	v_mfma_f32_32x32x16_bf16 v[98:113], v[138:141], v[162:165], v[98:113]
	v_add_f32_e32 v138, v72, v142
	v_add_f32_e32 v138, v73, v138
	v_add_f32_e32 v138, v74, v138
	v_add_f32_e32 v138, v75, v138
	v_cvt_pk_bf16_f32 v152, v70, v71
	v_cvt_pk_bf16_f32 v153, v72, v73
	ds_read_b64_tr_b16 v[70:71], v220 offset:44032
	ds_read_b64_tr_b16 v[72:73], v220 offset:44544
	s_waitcnt lgkmcnt(14)
	v_mfma_f32_32x32x16_bf16 v[114:129], v[134:137], v[154:157], v[114:129]
	v_add_f32_e32 v134, v76, v138
	v_add_f32_e32 v134, v77, v134
	v_add_f32_e32 v134, v78, v134
	v_add_f32_e32 v134, v79, v134
	v_cvt_pk_bf16_f32 v146, v74, v75
	v_cvt_pk_bf16_f32 v147, v76, v77
	ds_read_b64_tr_b16 v[74:75], v220 offset:48128
	ds_read_b64_tr_b16 v[76:77], v220 offset:48640
	v_mfma_f32_32x32x16_bf16 v[98:113], v[130:133], v[154:157], v[98:113]
	v_add_f32_e32 v130, v80, v134
	v_add_f32_e32 v130, v81, v130
	v_add_f32_e32 v130, 0, v130
	v_cvt_pk_bf16_f32 v148, v78, v79
	v_cvt_pk_bf16_f32 v149, v80, v81
	v_lshl_add_u64 v[78:79], v[212:213], 0, s[50:51]
	s_mov_b32 s13, m0
	s_mov_b32 m0, s12
	s_nop 0
	global_load_lds_dwordx4 v[78:79], off
	s_mov_b32 m0, s13
	s_mov_b64 s[12:13], 0x1f0000
	s_cmp_lg_u32 0, -1
	v_lshl_add_u64 v[78:79], v[210:211], 0, s[12:13]
	s_cselect_b32 s12, 0, 0
	s_add_i32 s12, s12, s5
	s_add_i32 s5, s12, 0x8000
	s_mov_b32 s13, m0
	s_mov_b32 m0, s5
	s_nop 0
	global_load_lds_dwordx4 v[78:79], off
	s_mov_b32 m0, s13
	v_add_f32_e32 v190, v199, v130
	s_waitcnt lgkmcnt(14)
	v_mfma_f32_32x32x16_bf16 v[18:33], v[166:169], v[214:217], v[18:33]
	v_exp_f32_e32 v114, v114
	v_exp_f32_e32 v115, v115
	v_exp_f32_e32 v116, v116
	v_exp_f32_e32 v117, v117
	s_waitcnt lgkmcnt(12)
	v_mfma_f32_32x32x16_bf16 v[34:49], v[166:169], v[82:85], v[34:49]
	v_exp_f32_e32 v118, v118
	v_exp_f32_e32 v119, v119
	v_exp_f32_e32 v120, v120
	v_exp_f32_e32 v121, v121
	ds_read_b128 v[78:81], v219 offset:8192
	ds_read_b128 v[178:181], v219 offset:8704
	s_waitcnt lgkmcnt(12)
	v_mfma_f32_32x32x16_bf16 v[18:33], v[158:161], v[86:89], v[18:33]
	v_exp_f32_e32 v122, v122
	v_exp_f32_e32 v123, v123
	v_exp_f32_e32 v124, v124
	v_exp_f32_e32 v125, v125
	ds_read_b128 v[86:89], v219 offset:10240
	ds_read_b128 v[182:185], v219 offset:10752
	s_waitcnt lgkmcnt(12)
	v_mfma_f32_32x32x16_bf16 v[34:49], v[158:161], v[90:93], v[34:49]
	v_exp_f32_e32 v126, v126
	v_exp_f32_e32 v127, v127
	v_exp_f32_e32 v128, v128
	v_exp_f32_e32 v129, v129
	ds_read_b128 v[90:93], v219 offset:12288
	ds_read_b128 v[186:189], v219 offset:12800
	s_waitcnt lgkmcnt(12)
	v_mfma_f32_32x32x16_bf16 v[18:33], v[150:153], v[94:97], v[18:33]
	v_exp_f32_e32 v98, v98
	v_exp_f32_e32 v99, v99
	v_exp_f32_e32 v100, v100
	v_exp_f32_e32 v101, v101
	ds_read_b128 v[94:97], v219 offset:14336
	ds_read_b128 v[82:85], v219 offset:14848
	s_waitcnt lgkmcnt(12)
	v_mfma_f32_32x32x16_bf16 v[34:49], v[150:153], v[66:69], v[34:49]
	v_exp_f32_e32 v102, v102
	v_exp_f32_e32 v103, v103
	v_exp_f32_e32 v104, v104
	v_exp_f32_e32 v105, v105
	s_waitcnt lgkmcnt(10)
	v_mfma_f32_32x32x16_bf16 v[18:33], v[146:149], v[70:73], v[18:33]
	v_exp_f32_e32 v106, v106
	v_exp_f32_e32 v107, v107
	v_exp_f32_e32 v108, v108
	v_exp_f32_e32 v109, v109
	s_waitcnt lgkmcnt(8)
	v_mfma_f32_32x32x16_bf16 v[34:49], v[146:149], v[74:77], v[34:49]
	v_exp_f32_e32 v110, v110
	v_exp_f32_e32 v111, v111
	v_exp_f32_e32 v112, v112
	v_exp_f32_e32 v113, v113
	s_waitcnt vmcnt(2) lgkmcnt(0)
	s_barrier
;   #define RESC() do{}while(0)
;   #define ROT() do{sl_prev=sl_cur;sl_cur=sl_next;sl_next=(sl_next==(NSLOT-1)*SLOTB)?0:sl_next+SLOTB;}while(0)
;   #define ENDW(tt) do{ if((tt)+3<NT){WAIT_BAR(2);} else if((tt)+2<NT){WAIT_BAR(1);} else {WAIT_BAR(0);} }while(0)
; template<int THRL> __device__ __forceinline__ void attn_unit(int b,int h,int qb,const bf16*Q,const bf16*__restrict__ K,const bf16*__restrict__ V,bf16*O,char*shm,float m2){
;     ...
;   for(;t+1<NT;t+=2){
;     STEP(pB0,pB1,pA0,pA1,t,(t+3<NT),(t+1<NT),(t+1<NT));       ENDW(t);   RESC(); ROT();
;     STEP(pA0,pA1,pB0,pB1,t+1,(t+4<NT),(t+2<NT),(t+2<NT));     ENDW(t+1); RESC(); ROT();
	ds_read_b64_tr_b16 v[214:215], v220 offset:24576
	ds_read_b64_tr_b16 v[216:217], v220 offset:25088
	v_add_f32_e32 v66, v114, v115
	v_add_f32_e32 v66, v116, v66
	v_add_f32_e32 v66, v117, v66
	v_add_f32_e32 v66, v118, v66
	v_add_f32_e32 v66, v119, v66
	v_cvt_pk_bf16_f32 v166, v114, v115
	v_cvt_pk_bf16_f32 v167, v116, v117
	s_waitcnt lgkmcnt(9)
	v_mfma_f32_32x32x16_bf16 v[130:145], v[78:81], v[174:177], v[50:65]
	ds_read_b64_tr_b16 v[114:115], v220 offset:28672
	ds_read_b64_tr_b16 v[116:117], v220 offset:29184
	v_add_f32_e32 v66, v120, v66
	v_add_f32_e32 v66, v121, v66
	v_add_f32_e32 v66, v122, v66
	v_add_f32_e32 v146, v123, v66
	s_waitcnt lgkmcnt(10)
	v_mfma_f32_32x32x16_bf16 v[66:81], v[178:181], v[174:177], v[50:65]
	v_cvt_pk_bf16_f32 v168, v118, v119
	v_cvt_pk_bf16_f32 v169, v120, v121
	ds_read_b64_tr_b16 v[118:119], v220 offset:25600
	ds_read_b64_tr_b16 v[120:121], v220 offset:26112
	s_waitcnt lgkmcnt(11)
	v_mfma_f32_32x32x16_bf16 v[130:145], v[86:89], v[170:173], v[130:145]
	v_add_f32_e32 v86, v124, v146
	v_add_f32_e32 v86, v125, v86
	v_add_f32_e32 v86, v126, v86
	v_add_f32_e32 v146, v127, v86
	v_cvt_pk_bf16_f32 v158, v122, v123
	v_cvt_pk_bf16_f32 v159, v124, v125
	ds_read_b64_tr_b16 v[86:87], v220 offset:29696
	ds_read_b64_tr_b16 v[88:89], v220 offset:30208
	s_waitcnt lgkmcnt(12)
	v_mfma_f32_32x32x16_bf16 v[66:81], v[182:185], v[170:173], v[66:81]
	v_add_f32_e32 v122, v128, v146
	v_add_f32_e32 v122, v129, v122
	v_add_f32_e32 v122, v98, v122
	v_add_f32_e32 v146, v99, v122
	v_cvt_pk_bf16_f32 v160, v126, v127
	v_cvt_pk_bf16_f32 v161, v128, v129
	ds_read_b64_tr_b16 v[122:123], v220 offset:26624
	ds_read_b64_tr_b16 v[124:125], v220 offset:27136
	s_waitcnt lgkmcnt(13)
	v_mfma_f32_32x32x16_bf16 v[130:145], v[90:93], v[162:165], v[130:145]
	v_add_f32_e32 v90, v100, v146
	v_add_f32_e32 v90, v101, v90
	v_add_f32_e32 v90, v102, v90
	v_add_f32_e32 v126, v103, v90
	v_cvt_pk_bf16_f32 v150, v98, v99
	v_cvt_pk_bf16_f32 v151, v100, v101
	ds_read_b64_tr_b16 v[90:91], v220 offset:30720
	ds_read_b64_tr_b16 v[92:93], v220 offset:31232
	s_waitcnt lgkmcnt(14)
	v_mfma_f32_32x32x16_bf16 v[66:81], v[186:189], v[162:165], v[66:81]
	v_add_f32_e32 v98, v104, v126
	v_add_f32_e32 v98, v105, v98
	v_add_f32_e32 v98, v106, v98
	v_add_f32_e32 v98, v107, v98
	v_cvt_pk_bf16_f32 v152, v102, v103
	v_cvt_pk_bf16_f32 v153, v104, v105
	ds_read_b64_tr_b16 v[102:103], v220 offset:27648
	ds_read_b64_tr_b16 v[104:105], v220 offset:28160
	s_waitcnt lgkmcnt(14)
	v_mfma_f32_32x32x16_bf16 v[130:145], v[94:97], v[154:157], v[130:145]
	v_add_f32_e32 v94, v108, v98
	v_add_f32_e32 v94, v109, v94
	v_add_f32_e32 v94, v110, v94
	v_add_f32_e32 v98, v111, v94
	v_cvt_pk_bf16_f32 v146, v106, v107
	v_cvt_pk_bf16_f32 v147, v108, v109
	ds_read_b64_tr_b16 v[94:95], v220 offset:31744
	ds_read_b64_tr_b16 v[96:97], v220 offset:32256
	v_mfma_f32_32x32x16_bf16 v[66:81], v[82:85], v[154:157], v[66:81]
	v_add_f32_e32 v82, v112, v98
	v_add_f32_e32 v82, v113, v82
	v_add_f32_e32 v82, 0, v82
	v_cvt_pk_bf16_f32 v148, v110, v111
	v_cvt_pk_bf16_f32 v149, v112, v113
	s_nop 0
	v_add_f32_e32 v190, v190, v82
	v_lshl_add_u64 v[82:83], v[212:213], 0, s[52:53]
	s_add_i32 s13, s12, 0x2000
	s_mov_b32 s14, m0
	s_mov_b32 m0, s13
	s_nop 0
	global_load_lds_dwordx4 v[82:83], off
	s_mov_b32 m0, s14
	s_mov_b64 s[14:15], 0x1f4000
	v_lshl_add_u64 v[82:83], v[210:211], 0, s[14:15]
	s_add_i32 s12, s12, 0xa000
	s_mov_b32 s13, m0
	s_mov_b32 m0, s12
	s_nop 0
	global_load_lds_dwordx4 v[82:83], off
	s_mov_b32 m0, s13
	s_waitcnt lgkmcnt(14)
	v_mfma_f32_32x32x16_bf16 v[18:33], v[166:169], v[214:217], v[18:33]
	v_exp_f32_e32 v130, v130
	v_exp_f32_e32 v131, v131
	v_exp_f32_e32 v132, v132
	v_exp_f32_e32 v133, v133
	s_waitcnt lgkmcnt(12)
	v_mfma_f32_32x32x16_bf16 v[34:49], v[166:169], v[114:117], v[34:49]
	v_exp_f32_e32 v134, v134
	v_exp_f32_e32 v135, v135
	v_exp_f32_e32 v136, v136
	v_exp_f32_e32 v137, v137
	ds_read_b128 v[82:85], v219 offset:16384
	ds_read_b128 v[106:109], v219 offset:16896
	s_waitcnt lgkmcnt(12)
	v_mfma_f32_32x32x16_bf16 v[18:33], v[158:161], v[118:121], v[18:33]
	v_exp_f32_e32 v138, v138
	v_exp_f32_e32 v139, v139
	v_exp_f32_e32 v140, v140
	v_exp_f32_e32 v141, v141
	ds_read_b128 v[110:113], v219 offset:18432
	ds_read_b128 v[178:181], v219 offset:18944
	s_waitcnt lgkmcnt(12)
	v_mfma_f32_32x32x16_bf16 v[34:49], v[158:161], v[86:89], v[34:49]
	v_exp_f32_e32 v142, v142
	v_exp_f32_e32 v143, v143
	v_exp_f32_e32 v144, v144
	v_exp_f32_e32 v145, v145
	ds_read_b128 v[182:185], v219 offset:20480
	ds_read_b128 v[186:189], v219 offset:20992
	s_waitcnt lgkmcnt(12)
	v_mfma_f32_32x32x16_bf16 v[18:33], v[150:153], v[122:125], v[18:33]
	v_exp_f32_e32 v66, v66
	v_exp_f32_e32 v67, v67
	v_exp_f32_e32 v68, v68
	v_exp_f32_e32 v69, v69
	ds_read_b128 v[212:215], v219 offset:22528
	ds_read_b128 v[98:101], v219 offset:23040
	s_waitcnt lgkmcnt(12)
	v_mfma_f32_32x32x16_bf16 v[34:49], v[150:153], v[90:93], v[34:49]
	v_exp_f32_e32 v70, v70
	v_exp_f32_e32 v71, v71
	v_exp_f32_e32 v72, v72
	v_exp_f32_e32 v73, v73
	s_waitcnt lgkmcnt(10)
	v_mfma_f32_32x32x16_bf16 v[18:33], v[146:149], v[102:105], v[18:33]
	v_exp_f32_e32 v74, v74
	v_exp_f32_e32 v75, v75
	v_exp_f32_e32 v76, v76
	v_exp_f32_e32 v77, v77
	s_waitcnt lgkmcnt(8)
	v_mfma_f32_32x32x16_bf16 v[34:49], v[146:149], v[94:97], v[34:49]
	v_exp_f32_e32 v78, v78
	v_exp_f32_e32 v79, v79
	v_exp_f32_e32 v80, v80
	v_exp_f32_e32 v81, v81
	s_waitcnt vmcnt(2) lgkmcnt(0)
	s_barrier
;   #define RESC() do{}while(0)
;   #define ROT() do{sl_prev=sl_cur;sl_cur=sl_next;sl_next=(sl_next==(NSLOT-1)*SLOTB)?0:sl_next+SLOTB;}while(0)
;   #define ENDW(tt) do{ if((tt)+3<NT){WAIT_BAR(2);} else if((tt)+2<NT){WAIT_BAR(1);} else {WAIT_BAR(0);} }while(0)
; template<int THRL> __device__ __forceinline__ void attn_unit(int b,int h,int qb,const bf16*Q,const bf16*__restrict__ K,const bf16*__restrict__ V,bf16*O,char*shm,float m2){
;     ...
;   for(;t+1<NT;t+=2){
;     STEP(pB0,pB1,pA0,pA1,t,(t+3<NT),(t+1<NT),(t+1<NT));       ENDW(t);   RESC(); ROT();
;     STEP(pA0,pA1,pB0,pB1,t+1,(t+4<NT),(t+2<NT),(t+2<NT));     ENDW(t+1); RESC(); ROT();
	ds_read_b64_tr_b16 v[102:103], v220 offset:32768
	ds_read_b64_tr_b16 v[104:105], v220 offset:33280
	v_add_f32_e32 v86, v130, v131
	v_add_f32_e32 v86, v132, v86
	v_add_f32_e32 v86, v133, v86
	v_add_f32_e32 v86, v134, v86
	v_add_f32_e32 v86, v135, v86
	v_cvt_pk_bf16_f32 v166, v130, v131
	v_cvt_pk_bf16_f32 v167, v132, v133
	s_waitcnt lgkmcnt(9)
	v_mfma_f32_32x32x16_bf16 v[114:129], v[82:85], v[174:177], v[50:65]
	ds_read_b64_tr_b16 v[130:131], v220 offset:36864
	ds_read_b64_tr_b16 v[132:133], v220 offset:37376
	v_add_f32_e32 v82, v136, v86
	v_add_f32_e32 v82, v137, v82
	v_add_f32_e32 v82, v138, v82
	v_add_f32_e32 v146, v139, v82
	v_cvt_pk_bf16_f32 v168, v134, v135
	v_cvt_pk_bf16_f32 v169, v136, v137
	s_waitcnt lgkmcnt(10)
	v_mfma_f32_32x32x16_bf16 v[82:97], v[106:109], v[174:177], v[50:65]
	ds_read_b64_tr_b16 v[106:107], v220 offset:33792
	ds_read_b64_tr_b16 v[108:109], v220 offset:34304
	s_waitcnt lgkmcnt(11)
	v_mfma_f32_32x32x16_bf16 v[114:129], v[110:113], v[170:173], v[114:129]
	v_add_f32_e32 v110, v140, v146
	v_add_f32_e32 v110, v141, v110
	v_add_f32_e32 v110, v142, v110
	v_add_f32_e32 v134, v143, v110
	v_cvt_pk_bf16_f32 v158, v138, v139
	v_cvt_pk_bf16_f32 v159, v140, v141
	ds_read_b64_tr_b16 v[110:111], v220 offset:37888
	ds_read_b64_tr_b16 v[112:113], v220 offset:38400
	v_add_f32_e32 v134, v144, v134
	v_add_f32_e32 v134, v145, v134
	v_add_f32_e32 v134, v66, v134
	v_add_f32_e32 v138, v67, v134
	v_cvt_pk_bf16_f32 v160, v142, v143
	v_cvt_pk_bf16_f32 v161, v144, v145
	s_waitcnt lgkmcnt(12)
	v_mfma_f32_32x32x16_bf16 v[82:97], v[178:181], v[170:173], v[82:97]
	ds_read_b64_tr_b16 v[134:135], v220 offset:34816
	ds_read_b64_tr_b16 v[136:137], v220 offset:35328
	v_add_f32_e32 v138, v68, v138
	v_add_f32_e32 v138, v69, v138
	v_add_f32_e32 v138, v70, v138
	v_add_f32_e32 v138, v71, v138
	v_cvt_pk_bf16_f32 v150, v66, v67
	v_cvt_pk_bf16_f32 v151, v68, v69
	s_waitcnt lgkmcnt(13)
	v_mfma_f32_32x32x16_bf16 v[114:129], v[182:185], v[162:165], v[114:129]
	ds_read_b64_tr_b16 v[66:67], v220 offset:38912
	ds_read_b64_tr_b16 v[68:69], v220 offset:39424
	v_add_f32_e32 v138, v72, v138
	v_add_f32_e32 v138, v73, v138
	v_add_f32_e32 v138, v74, v138
	v_add_f32_e32 v138, v75, v138
	v_cvt_pk_bf16_f32 v152, v70, v71
	v_cvt_pk_bf16_f32 v153, v72, v73
	s_waitcnt lgkmcnt(14)
	v_mfma_f32_32x32x16_bf16 v[82:97], v[186:189], v[162:165], v[82:97]
	ds_read_b64_tr_b16 v[70:71], v220 offset:35840
	ds_read_b64_tr_b16 v[72:73], v220 offset:36352
	v_add_f32_e32 v138, v76, v138
	v_add_f32_e32 v138, v77, v138
	v_add_f32_e32 v138, v78, v138
	v_add_f32_e32 v138, v79, v138
	v_cvt_pk_bf16_f32 v146, v74, v75
	v_cvt_pk_bf16_f32 v147, v76, v77
	s_waitcnt lgkmcnt(14)
	v_mfma_f32_32x32x16_bf16 v[114:129], v[212:215], v[154:157], v[114:129]
	ds_read_b64_tr_b16 v[74:75], v220 offset:39936
	ds_read_b64_tr_b16 v[76:77], v220 offset:40448
	v_mfma_f32_32x32x16_bf16 v[82:97], v[98:101], v[154:157], v[82:97]
	v_add_f32_e32 v98, v80, v138
	v_add_f32_e32 v98, v81, v98
	v_add_f32_e32 v98, 0, v98
	v_cvt_pk_bf16_f32 v148, v78, v79
	v_cvt_pk_bf16_f32 v149, v80, v81
	v_lshl_add_u64 v[78:79], v[210:211], 0, s[50:51]
	s_mov_b32 s12, m0
	s_mov_b32 m0, s4
	s_nop 0
	global_load_lds_dwordx4 v[78:79], off
	s_mov_b32 m0, s12
	v_add_f32_e32 v190, v190, v98
	s_waitcnt lgkmcnt(14)
	v_mfma_f32_32x32x16_bf16 v[18:33], v[166:169], v[102:105], v[18:33]
	v_exp_f32_e32 v114, v114
	v_exp_f32_e32 v115, v115
	v_exp_f32_e32 v116, v116
	v_exp_f32_e32 v117, v117
	s_waitcnt lgkmcnt(12)
	v_mfma_f32_32x32x16_bf16 v[34:49], v[166:169], v[130:133], v[34:49]
	v_exp_f32_e32 v118, v118
	v_exp_f32_e32 v119, v119
	v_exp_f32_e32 v120, v120
	v_exp_f32_e32 v121, v121
	ds_read_b128 v[78:81], v219
	ds_read_b128 v[138:141], v219 offset:512
	s_waitcnt lgkmcnt(12)
	v_mfma_f32_32x32x16_bf16 v[18:33], v[158:161], v[106:109], v[18:33]
	v_exp_f32_e32 v122, v122
	v_exp_f32_e32 v123, v123
	v_exp_f32_e32 v124, v124
	v_exp_f32_e32 v125, v125
	ds_read_b128 v[142:145], v219 offset:2048
	ds_read_b128 v[178:181], v219 offset:2560
	s_waitcnt lgkmcnt(12)
	v_mfma_f32_32x32x16_bf16 v[34:49], v[158:161], v[110:113], v[34:49]
	v_exp_f32_e32 v126, v126
	v_exp_f32_e32 v127, v127
	v_exp_f32_e32 v128, v128
	v_exp_f32_e32 v129, v129
	ds_read_b128 v[182:185], v219 offset:4096
	ds_read_b128 v[186:189], v219 offset:4608
	s_waitcnt lgkmcnt(12)
	v_mfma_f32_32x32x16_bf16 v[18:33], v[150:153], v[134:137], v[18:33]
	v_exp_f32_e32 v82, v82
	v_exp_f32_e32 v83, v83
	v_exp_f32_e32 v84, v84
	v_exp_f32_e32 v85, v85
	ds_read_b128 v[134:137], v219 offset:6144
	ds_read_b128 v[130:133], v219 offset:6656
	s_waitcnt lgkmcnt(12)
	v_mfma_f32_32x32x16_bf16 v[34:49], v[150:153], v[66:69], v[34:49]
	v_exp_f32_e32 v86, v86
	v_exp_f32_e32 v87, v87
	v_exp_f32_e32 v88, v88
	v_exp_f32_e32 v89, v89
	s_waitcnt lgkmcnt(10)
	v_mfma_f32_32x32x16_bf16 v[18:33], v[146:149], v[70:73], v[18:33]
	v_exp_f32_e32 v90, v90
	v_exp_f32_e32 v91, v91
	v_exp_f32_e32 v92, v92
	v_exp_f32_e32 v93, v93
	s_waitcnt lgkmcnt(8)
	v_mfma_f32_32x32x16_bf16 v[34:49], v[146:149], v[74:77], v[34:49]
	v_exp_f32_e32 v94, v94
	v_exp_f32_e32 v95, v95
	v_exp_f32_e32 v96, v96
	v_exp_f32_e32 v97, v97
	s_waitcnt vmcnt(1) lgkmcnt(0)
	s_barrier
;   #define RESC() do{}while(0)
;   #define ROT() do{sl_prev=sl_cur;sl_cur=sl_next;sl_next=(sl_next==(NSLOT-1)*SLOTB)?0:sl_next+SLOTB;}while(0)
;   #define ENDW(tt) do{ if((tt)+3<NT){WAIT_BAR(2);} else if((tt)+2<NT){WAIT_BAR(1);} else {WAIT_BAR(0);} }while(0)
; template<int THRL> __device__ __forceinline__ void attn_unit(int b,int h,int qb,const bf16*Q,const bf16*__restrict__ K,const bf16*__restrict__ V,bf16*O,char*shm,float m2){
;     ...
;   for(;t+1<NT;t+=2){
;     STEP(pB0,pB1,pA0,pA1,t,(t+3<NT),(t+1<NT),(t+1<NT));       ENDW(t);   RESC(); ROT();
;     STEP(pA0,pA1,pB0,pB1,t+1,(t+4<NT),(t+2<NT),(t+2<NT));     ENDW(t+1); RESC(); ROT();
	ds_read_b64_tr_b16 v[212:213], v220 offset:40960
	ds_read_b64_tr_b16 v[214:215], v220 offset:41472
	v_add_f32_e32 v66, v114, v115
	v_add_f32_e32 v66, v116, v66
	v_add_f32_e32 v66, v117, v66
	v_add_f32_e32 v66, v118, v66
	v_add_f32_e32 v66, v119, v66
	v_cvt_pk_bf16_f32 v166, v114, v115
	v_cvt_pk_bf16_f32 v167, v116, v117
	s_waitcnt lgkmcnt(9)
	v_mfma_f32_32x32x16_bf16 v[98:113], v[78:81], v[174:177], v[50:65]
	ds_read_b64_tr_b16 v[114:115], v220 offset:45056
	ds_read_b64_tr_b16 v[116:117], v220 offset:45568
	v_add_f32_e32 v66, v120, v66
	v_add_f32_e32 v66, v121, v66
	v_add_f32_e32 v66, v122, v66
	v_add_f32_e32 v146, v123, v66
	s_waitcnt lgkmcnt(10)
	v_mfma_f32_32x32x16_bf16 v[66:81], v[138:141], v[174:177], v[50:65]
	v_cvt_pk_bf16_f32 v168, v118, v119
	v_cvt_pk_bf16_f32 v169, v120, v121
	ds_read_b64_tr_b16 v[138:139], v220 offset:41984
	ds_read_b64_tr_b16 v[140:141], v220 offset:42496
	v_add_f32_e32 v118, v124, v146
	v_add_f32_e32 v118, v125, v118
	v_add_f32_e32 v118, v126, v118
	v_add_f32_e32 v118, v127, v118
	v_cvt_pk_bf16_f32 v158, v122, v123
	v_cvt_pk_bf16_f32 v159, v124, v125
	s_waitcnt lgkmcnt(11)
	v_mfma_f32_32x32x16_bf16 v[98:113], v[142:145], v[170:173], v[98:113]
	ds_read_b64_tr_b16 v[120:121], v220 offset:46080
	ds_read_b64_tr_b16 v[122:123], v220 offset:46592
	s_waitcnt lgkmcnt(12)
	v_mfma_f32_32x32x16_bf16 v[66:81], v[178:181], v[170:173], v[66:81]
	v_add_f32_e32 v118, v128, v118
	v_add_f32_e32 v118, v129, v118
	v_add_f32_e32 v118, v82, v118
	v_add_f32_e32 v118, v83, v118
	v_cvt_pk_bf16_f32 v160, v126, v127
	v_cvt_pk_bf16_f32 v161, v128, v129
	ds_read_b64_tr_b16 v[124:125], v220 offset:43008
	ds_read_b64_tr_b16 v[126:127], v220 offset:43520
	v_add_f32_e32 v118, v84, v118
	v_add_f32_e32 v118, v85, v118
	v_add_f32_e32 v118, v86, v118
	v_add_f32_e32 v118, v87, v118
	v_cvt_pk_bf16_f32 v150, v82, v83
	v_cvt_pk_bf16_f32 v151, v84, v85
	s_waitcnt lgkmcnt(13)
	v_mfma_f32_32x32x16_bf16 v[98:113], v[182:185], v[162:165], v[98:113]
	ds_read_b64_tr_b16 v[82:83], v220 offset:47104
	ds_read_b64_tr_b16 v[84:85], v220 offset:47616
	s_waitcnt lgkmcnt(14)
	v_mfma_f32_32x32x16_bf16 v[66:81], v[186:189], v[162:165], v[66:81]
	v_add_f32_e32 v118, v88, v118
	v_add_f32_e32 v118, v89, v118
	v_add_f32_e32 v118, v90, v118
	v_add_f32_e32 v118, v91, v118
	v_cvt_pk_bf16_f32 v152, v86, v87
	v_cvt_pk_bf16_f32 v153, v88, v89
	ds_read_b64_tr_b16 v[86:87], v220 offset:44032
	ds_read_b64_tr_b16 v[88:89], v220 offset:44544
	v_add_f32_e32 v118, v92, v118
	v_add_f32_e32 v118, v93, v118
	v_add_f32_e32 v118, v94, v118
	v_add_f32_e32 v118, v95, v118
	v_cvt_pk_bf16_f32 v146, v90, v91
	v_cvt_pk_bf16_f32 v147, v92, v93
	s_waitcnt lgkmcnt(14)
	v_mfma_f32_32x32x16_bf16 v[98:113], v[134:137], v[154:157], v[98:113]
	ds_read_b64_tr_b16 v[90:91], v220 offset:48128
	ds_read_b64_tr_b16 v[92:93], v220 offset:48640
	v_mfma_f32_32x32x16_bf16 v[66:81], v[130:133], v[154:157], v[66:81]
	v_add_f32_e32 v118, v96, v118
	v_add_f32_e32 v118, v97, v118
	v_add_f32_e32 v118, 0, v118
	v_cvt_pk_bf16_f32 v148, v94, v95
	v_cvt_pk_bf16_f32 v149, v96, v97
	v_lshl_add_u64 v[94:95], v[210:211], 0, s[52:53]
	s_mov_b32 s4, m0
	s_mov_b32 m0, s5
	s_nop 0
	global_load_lds_dwordx4 v[94:95], off
	s_mov_b32 m0, s4
	v_add_f32_e32 v118, v190, v118
	s_waitcnt lgkmcnt(14)
	v_mfma_f32_32x32x16_bf16 v[18:33], v[166:169], v[212:215], v[18:33]
	v_exp_f32_e32 v98, v98
	v_exp_f32_e32 v99, v99
	v_exp_f32_e32 v100, v100
	v_exp_f32_e32 v101, v101
	s_waitcnt lgkmcnt(12)
	v_mfma_f32_32x32x16_bf16 v[34:49], v[166:169], v[114:117], v[34:49]
	v_exp_f32_e32 v102, v102
	v_exp_f32_e32 v103, v103
	v_exp_f32_e32 v104, v104
	v_exp_f32_e32 v105, v105
	ds_read_b128 v[128:131], v219 offset:8192
	ds_read_b128 v[132:135], v219 offset:8704
	s_waitcnt lgkmcnt(12)
	v_mfma_f32_32x32x16_bf16 v[18:33], v[158:161], v[138:141], v[18:33]
	v_exp_f32_e32 v106, v106
	v_exp_f32_e32 v107, v107
	v_exp_f32_e32 v108, v108
	v_exp_f32_e32 v109, v109
	ds_read_b128 v[136:139], v219 offset:10240
	ds_read_b128 v[140:143], v219 offset:10752
	s_waitcnt lgkmcnt(12)
	v_mfma_f32_32x32x16_bf16 v[34:49], v[158:161], v[120:123], v[34:49]
	v_exp_f32_e32 v110, v110
	v_exp_f32_e32 v111, v111
	v_exp_f32_e32 v112, v112
	v_exp_f32_e32 v113, v113
	ds_read_b128 v[120:123], v219 offset:12288
	ds_read_b128 v[178:181], v219 offset:12800
	s_waitcnt lgkmcnt(12)
	v_mfma_f32_32x32x16_bf16 v[18:33], v[150:153], v[124:127], v[18:33]
	v_exp_f32_e32 v66, v66
	v_exp_f32_e32 v67, v67
	v_exp_f32_e32 v68, v68
	v_exp_f32_e32 v69, v69
	ds_read_b128 v[124:127], v219 offset:14336
	ds_read_b128 v[114:117], v219 offset:14848
	s_waitcnt lgkmcnt(12)
	v_mfma_f32_32x32x16_bf16 v[34:49], v[150:153], v[82:85], v[34:49]
	v_exp_f32_e32 v70, v70
	v_exp_f32_e32 v71, v71
	v_exp_f32_e32 v72, v72
	v_exp_f32_e32 v73, v73
	s_waitcnt lgkmcnt(10)
	v_mfma_f32_32x32x16_bf16 v[18:33], v[146:149], v[86:89], v[18:33]
	v_exp_f32_e32 v74, v74
	v_exp_f32_e32 v75, v75
	v_exp_f32_e32 v76, v76
	v_exp_f32_e32 v77, v77
	s_waitcnt lgkmcnt(8)
	v_mfma_f32_32x32x16_bf16 v[34:49], v[146:149], v[90:93], v[34:49]
	v_exp_f32_e32 v78, v78
	v_exp_f32_e32 v79, v79
	v_exp_f32_e32 v80, v80
	v_exp_f32_e32 v81, v81
	s_waitcnt vmcnt(0) lgkmcnt(0)
	s_barrier
;   #define RESC() do{}while(0)
; template<int THRL> __device__ __forceinline__ void attn_unit(int b,int h,int qb,const bf16*Q,const bf16*__restrict__ K,const bf16*__restrict__ V,bf16*O,char*shm,float m2){
;     ...
;   STEP(pB0,pB1,pA0,pA1,NT-1,false,false,false); RESC();
	ds_read_b64_tr_b16 v[182:183], v220 offset:24576
	ds_read_b64_tr_b16 v[184:185], v220 offset:25088
	v_add_f32_e32 v82, v98, v99
	v_add_f32_e32 v82, v100, v82
	v_add_f32_e32 v82, v101, v82
	v_add_f32_e32 v82, v102, v82
	v_add_f32_e32 v119, v103, v82
	v_cvt_pk_bf16_f32 v166, v98, v99
	v_cvt_pk_bf16_f32 v167, v100, v101
	s_waitcnt lgkmcnt(9)
	v_mfma_f32_32x32x16_bf16 v[82:97], v[128:131], v[174:177], v[50:65]
	ds_read_b64_tr_b16 v[98:99], v220 offset:28672
	ds_read_b64_tr_b16 v[100:101], v220 offset:29184
	s_waitcnt lgkmcnt(10)
	v_mfma_f32_32x32x16_bf16 v[50:65], v[132:135], v[174:177], v[50:65]
	v_add_f32_e32 v119, v104, v119
	v_add_f32_e32 v119, v105, v119
	v_add_f32_e32 v119, v106, v119
	v_add_f32_e32 v119, v107, v119
	v_cvt_pk_bf16_f32 v168, v102, v103
	v_cvt_pk_bf16_f32 v169, v104, v105
	ds_read_b64_tr_b16 v[102:103], v220 offset:25600
	ds_read_b64_tr_b16 v[104:105], v220 offset:26112
	v_add_f32_e32 v119, v108, v119
	v_add_f32_e32 v119, v109, v119
	v_add_f32_e32 v119, v110, v119
	v_add_f32_e32 v119, v111, v119
	v_cvt_pk_bf16_f32 v158, v106, v107
	v_cvt_pk_bf16_f32 v159, v108, v109
	s_waitcnt lgkmcnt(11)
	v_mfma_f32_32x32x16_bf16 v[82:97], v[136:139], v[170:173], v[82:97]
	ds_read_b64_tr_b16 v[106:107], v220 offset:29696
	ds_read_b64_tr_b16 v[108:109], v220 offset:30208
	s_waitcnt lgkmcnt(12)
	v_mfma_f32_32x32x16_bf16 v[50:65], v[140:143], v[170:173], v[50:65]
	v_add_f32_e32 v119, v112, v119
	v_add_f32_e32 v119, v113, v119
	v_add_f32_e32 v119, v66, v119
	v_add_f32_e32 v119, v67, v119
	v_cvt_pk_bf16_f32 v160, v110, v111
	v_cvt_pk_bf16_f32 v161, v112, v113
	ds_read_b64_tr_b16 v[110:111], v220 offset:26624
	ds_read_b64_tr_b16 v[112:113], v220 offset:27136
	v_add_f32_e32 v119, v68, v119
	v_add_f32_e32 v119, v69, v119
	v_add_f32_e32 v119, v70, v119
	v_add_f32_e32 v119, v71, v119
	v_cvt_pk_bf16_f32 v150, v66, v67
	v_cvt_pk_bf16_f32 v151, v68, v69
	s_waitcnt lgkmcnt(13)
	v_mfma_f32_32x32x16_bf16 v[82:97], v[120:123], v[162:165], v[82:97]
	ds_read_b64_tr_b16 v[66:67], v220 offset:30720
	ds_read_b64_tr_b16 v[68:69], v220 offset:31232
	s_waitcnt lgkmcnt(14)
	v_mfma_f32_32x32x16_bf16 v[50:65], v[178:181], v[162:165], v[50:65]
	v_add_f32_e32 v119, v72, v119
	v_add_f32_e32 v119, v73, v119
	v_add_f32_e32 v119, v74, v119
	v_add_f32_e32 v119, v75, v119
	v_cvt_pk_bf16_f32 v152, v70, v71
	v_cvt_pk_bf16_f32 v153, v72, v73
	ds_read_b64_tr_b16 v[70:71], v220 offset:27648
	ds_read_b64_tr_b16 v[72:73], v220 offset:28160
	v_add_f32_e32 v119, v76, v119
	v_add_f32_e32 v119, v77, v119
	v_add_f32_e32 v119, v78, v119
	v_add_f32_e32 v119, v79, v119
	v_cvt_pk_bf16_f32 v146, v74, v75
	v_cvt_pk_bf16_f32 v147, v76, v77
	s_waitcnt lgkmcnt(14)
	v_mfma_f32_32x32x16_bf16 v[82:97], v[124:127], v[154:157], v[82:97]
	ds_read_b64_tr_b16 v[74:75], v220 offset:31744
	ds_read_b64_tr_b16 v[76:77], v220 offset:32256
	v_mfma_f32_32x32x16_bf16 v[50:65], v[114:117], v[154:157], v[50:65]
	v_add_f32_e32 v114, v80, v119
	v_add_f32_e32 v114, v81, v114
	v_add_f32_e32 v114, 0, v114
	v_cvt_pk_bf16_f32 v148, v78, v79
	v_cvt_pk_bf16_f32 v149, v80, v81
	s_waitcnt lgkmcnt(14)
	v_mfma_f32_32x32x16_bf16 v[18:33], v[166:169], v[182:185], v[18:33]
	s_nop 1
	v_exp_f32_e32 v82, v82
	v_exp_f32_e32 v83, v83
	v_exp_f32_e32 v84, v84
	v_exp_f32_e32 v85, v85
	s_waitcnt lgkmcnt(12)
	v_mfma_f32_32x32x16_bf16 v[34:49], v[166:169], v[98:101], v[34:49]
	v_exp_f32_e32 v86, v86
	v_exp_f32_e32 v87, v87
	v_exp_f32_e32 v88, v88
	v_exp_f32_e32 v89, v89
	s_waitcnt lgkmcnt(10)
	v_mfma_f32_32x32x16_bf16 v[18:33], v[158:161], v[102:105], v[18:33]
	v_exp_f32_e32 v90, v90
	v_exp_f32_e32 v91, v91
	v_exp_f32_e32 v92, v92
	v_exp_f32_e32 v93, v93
	s_waitcnt lgkmcnt(8)
	v_mfma_f32_32x32x16_bf16 v[34:49], v[158:161], v[106:109], v[34:49]
	v_exp_f32_e32 v94, v94
	v_exp_f32_e32 v95, v95
	v_exp_f32_e32 v96, v96
	v_exp_f32_e32 v97, v97
	s_waitcnt lgkmcnt(6)
; #define SBAR() __builtin_amdgcn_sched_barrier(0)
; #define WAIT_BAR(N) asm volatile("s_waitcnt vmcnt(" #N ") lgkmcnt(0)\n\ts_barrier":::"memory")
;   #define RESC() do{}while(0)
;   #define ROT() do{sl_prev=sl_cur;sl_cur=sl_next;sl_next=(sl_next==(NSLOT-1)*SLOTB)?0:sl_next+SLOTB;}while(0)
;   #define PKW(P,B) cvtpk_s(P[B],P[B+1])
;   #define ENDW(tt) do{ if((tt)+3<NT){WAIT_BAR(2);} else if((tt)+2<NT){WAIT_BAR(1);} else {WAIT_BAR(0);} }while(0)
; template<int THRL> __device__ __forceinline__ void attn_unit(int b,int h,int qb,const bf16*Q,const bf16*__restrict__ K,const bf16*__restrict__ V,bf16*O,char*shm,float m2){
;     ...
;   int t=1;
;   for(;t+5<NT;t+=2){
;     STEP(pB0,pB1,pA0,pA1,t,true,true,true);     WAIT_BAR(2); RESC(); ROT();
;     STEP(pA0,pA1,pB0,pB1,t+1,true,true,true);   WAIT_BAR(2); RESC(); ROT();
;   }
;     ...
;   for(;t+1<NT;t+=2){
;     STEP(pB0,pB1,pA0,pA1,t,(t+3<NT),(t+1<NT),(t+1<NT));       ENDW(t);   RESC(); ROT();
;     STEP(pA0,pA1,pB0,pB1,t+1,(t+4<NT),(t+2<NT),(t+2<NT));     ENDW(t+1); RESC(); ROT();
;   }
;   STEP(pB0,pB1,pA0,pA1,NT-1,false,false,false); RESC();
;   { float sacc=pB0[0]+pB0[1]; _Pragma("unroll") for(int r=2;r<16;++r)sacc+=pB0[r]; _Pragma("unroll") for(int r=0;r<16;++r)sacc+=pB1[r]; l_reg+=sacc;
;     pw0=(u32x4){PKW(pB0,0),PKW(pB0,2),PKW(pB0,4),PKW(pB0,6)};pw1=(u32x4){PKW(pB0,8),PKW(pB0,10),PKW(pB0,12),PKW(pB0,14)};pw2=(u32x4){PKW(pB1,0),PKW(pB1,2),PKW(pB1,4),PKW(pB1,6)};pw3=(u32x4){PKW(pB1,8),PKW(pB1,10),PKW(pB1,12),PKW(pB1,14)};
;     SBAR(); pv(o,vb0+sl_cur,PAF(0),PAF(1),PAF(2),PAF(3)); }
;     ...
;   {auto rr=__builtin_amdgcn_permlane32_swap(__float_as_uint(l_reg),__float_as_uint(l_reg),false,false);l_reg=__uint_as_float(rr[0])+__uint_as_float(rr[1]);}
;   if(hi==0)wsf[32+r32]=l_reg;asm volatile("s_waitcnt lgkmcnt(0)":::"memory");
	v_mfma_f32_32x32x16_bf16 v[18:33], v[150:153], v[110:113], v[18:33]
	v_exp_f32_e32 v50, v50
	v_exp_f32_e32 v51, v51
	v_exp_f32_e32 v52, v52
	v_exp_f32_e32 v53, v53
	s_waitcnt lgkmcnt(4)
	v_mfma_f32_32x32x16_bf16 v[34:49], v[150:153], v[66:69], v[34:49]
	v_exp_f32_e32 v54, v54
	v_exp_f32_e32 v55, v55
	v_exp_f32_e32 v56, v56
	v_exp_f32_e32 v57, v57
	s_waitcnt lgkmcnt(2)
	v_mfma_f32_32x32x16_bf16 v[18:33], v[146:149], v[70:73], v[18:33]
	v_exp_f32_e32 v58, v58
	v_exp_f32_e32 v59, v59
	v_exp_f32_e32 v60, v60
	v_exp_f32_e32 v61, v61
	s_waitcnt lgkmcnt(0)
	v_mfma_f32_32x32x16_bf16 v[34:49], v[146:149], v[74:77], v[34:49]
	v_exp_f32_e32 v62, v62
	v_exp_f32_e32 v63, v63
	v_exp_f32_e32 v64, v64
	v_exp_f32_e32 v65, v65
	v_add_f32_e32 v66, v82, v83
	v_add_f32_e32 v66, v84, v66
	v_add_f32_e32 v66, v85, v66
	v_add_f32_e32 v66, v86, v66
	v_add_f32_e32 v66, v87, v66
	v_add_f32_e32 v66, v88, v66
	v_add_f32_e32 v66, v89, v66
	v_add_f32_e32 v66, v90, v66
	v_add_f32_e32 v66, v91, v66
	v_add_f32_e32 v66, v92, v66
	v_add_f32_e32 v66, v93, v66
	v_add_f32_e32 v66, v94, v66
	v_add_f32_e32 v66, v95, v66
	v_add_f32_e32 v66, v96, v66
	v_add_f32_e32 v66, v97, v66
	v_add_f32_e32 v66, v50, v66
	v_add_f32_e32 v66, v51, v66
	v_add_f32_e32 v66, v52, v66
	v_add_f32_e32 v66, v53, v66
	v_add_f32_e32 v66, v54, v66
	v_add_f32_e32 v66, v55, v66
	v_add_f32_e32 v66, v56, v66
	v_add_f32_e32 v66, v57, v66
	v_add_f32_e32 v66, v58, v66
	v_add_f32_e32 v66, v59, v66
	v_add_f32_e32 v66, v60, v66
	v_add_f32_e32 v66, v61, v66
	v_add_f32_e32 v66, v62, v66
	v_add_f32_e32 v66, v63, v66
	v_add_f32_e32 v66, v64, v66
	v_add_f32_e32 v66, v65, v66
	v_add_f32_e32 v67, v118, v114
	v_add_f32_e32 v66, v67, v66
	v_cvt_pk_bf16_f32 v50, v50, v51
	v_cvt_pk_bf16_f32 v68, v82, v83
	v_cvt_pk_bf16_f32 v69, v84, v85
	v_cvt_pk_bf16_f32 v70, v86, v87
	v_cvt_pk_bf16_f32 v71, v88, v89
	v_cvt_pk_bf16_f32 v72, v90, v91
	v_cvt_pk_bf16_f32 v73, v92, v93
	v_cvt_pk_bf16_f32 v74, v94, v95
	v_cvt_pk_bf16_f32 v75, v96, v97
	v_cvt_pk_bf16_f32 v51, v52, v53
	v_cvt_pk_bf16_f32 v52, v54, v55
	v_cvt_pk_bf16_f32 v53, v56, v57
	v_cvt_pk_bf16_f32 v54, v58, v59
	v_cvt_pk_bf16_f32 v55, v60, v61
	v_cvt_pk_bf16_f32 v56, v62, v63
	v_cvt_pk_bf16_f32 v57, v64, v65
	ds_read_b64_tr_b16 v[58:59],v221 offset:0
	ds_read_b64_tr_b16 v[60:61],v221 offset:512
	ds_read_b64_tr_b16 v[62:63],v221 offset:1024
	ds_read_b64_tr_b16 v[64:65],v221 offset:1536
	ds_read_b64_tr_b16 v[76:77],v221 offset:2048
	ds_read_b64_tr_b16 v[78:79],v221 offset:2560
	ds_read_b64_tr_b16 v[80:81],v221 offset:3072
	ds_read_b64_tr_b16 v[82:83],v221 offset:3584
	s_waitcnt lgkmcnt(0)
	s_nop 0
	v_mfma_f32_32x32x16_bf16 v[18:33], v[68:71], v[58:61], v[18:33]
	ds_read_b64_tr_b16 v[58:59],v221 offset:4096
	ds_read_b64_tr_b16 v[60:61],v221 offset:4608
	v_mfma_f32_32x32x16_bf16 v[18:33], v[72:75], v[62:65], v[18:33]
	ds_read_b64_tr_b16 v[62:63],v221 offset:5120
	ds_read_b64_tr_b16 v[64:65],v221 offset:5632
	v_mfma_f32_32x32x16_bf16 v[18:33], v[50:53], v[76:79], v[18:33]
	ds_read_b64_tr_b16 v[76:77],v221 offset:6144
	ds_read_b64_tr_b16 v[78:79],v221 offset:6656
	v_mfma_f32_32x32x16_bf16 v[18:33], v[54:57], v[80:83], v[18:33]
	ds_read_b64_tr_b16 v[80:81],v221 offset:7168
	ds_read_b64_tr_b16 v[82:83],v221 offset:7680
	s_waitcnt lgkmcnt(0)
	v_mfma_f32_32x32x16_bf16 v[34:49], v[68:71], v[58:61], v[34:49]
	v_mfma_f32_32x32x16_bf16 v[34:49], v[72:75], v[62:65], v[34:49]
	v_mfma_f32_32x32x16_bf16 v[34:49], v[50:53], v[76:79], v[34:49]
	v_mov_b32_e32 v50, v66
	s_nop 1
	v_permlane32_swap_b32_e32 v66, v50
	v_mfma_f32_32x32x16_bf16 v[34:49], v[54:57], v[80:83], v[34:49]
	s_and_saveexec_b64 s[4:5], s[2:3]
	s_cbranch_execz .LBB0_823
	v_add_f32_e32 v50, v66, v50
	v_lshl_add_u32 v51, v1, 2, s0
	ds_write_b32 v51, v50 offset:49280
	s_branch .LBB0_823
